# a5 + retention phases remapped so each XCD owns 2 (b,h) sequences end-to-end; B6,B7 XCD-local
# speedup vs baseline: 1.0127x; 1.0073x over previous
.LBB0_746:
	s_or_b64 exec, exec, s[0:1]
	s_add_u32 s12, s26, 0x6900000
	s_addc_u32 s13, s27, 0
	s_cmpk_lt_i32 s2, 0x400
	s_cselect_b64 s[6:7], -1, 0
	s_cmpk_gt_i32 s2, 0x3ff
	s_waitcnt lgkmcnt(0)
	s_barrier
	v_mbcnt_lo_u32_b32 v0, -1, 0
	v_mbcnt_hi_u32_b32 v0, -1, v0
	s_cbranch_scc1 .LBB0_753
	s_and_b32 s64, s2, 7
	s_lshl_b32 s64, s64, 7
	s_lshr_b32 s67, s2, 3
	s_or_b32 s64, s64, s67
	s_mov_b32 s66, 32
	s_cmp_eq_u32 s28, 0x100
	s_cselect_b32 s64, s64, s2
	s_cselect_b32 s66, s66, s28
	s_add_u32 s16, s26, 0x5900000
	s_addc_u32 s17, s27, 0
	s_ashr_i32 s0, s64, 9
	s_ashr_i32 s1, s0, 31
	s_lshl_b64 s[18:19], s[0:1], 13
	s_lshl_b32 s0, s64, 7
	v_add_u32_e32 v1, s33, v0
	s_bfe_u32 s20, s64, 0x30006
	s_and_b32 s0, s0, 0x1f80
	v_ashrrev_i32_e32 v66, 3, v1
	s_or_b32 s18, s18, s0
	s_lshl_b32 s0, s20, 7
	v_ashrrev_i32_e32 v67, 31, v66
	s_add_u32 s8, s16, s0
	v_lshlrev_b32_e32 v4, 4, v0
	v_lshl_add_u64 v[2:3], s[18:19], 0, v[66:67]
	s_addc_u32 s9, s17, 0
	v_and_b32_e32 v4, 0x70, v4
	v_mov_b32_e32 v5, 0
	v_lshl_add_u64 v[6:7], s[8:9], 0, v[4:5]
	v_lshlrev_b64 v[2:3], 10, v[2:3]
	v_lshl_add_u64 v[2:3], v[6:7], 0, v[2:3]
	s_mov_b32 s8, 0x10000
	v_and_b32_e32 v64, 0x7f, v1
	v_add_co_u32_e32 v6, vcc, s8, v2
	v_ashrrev_i32_e32 v8, 7, v1
	s_nop 0
	v_addc_co_u32_e32 v7, vcc, 0, v3, vcc
	global_load_dwordx4 v[32:35], v[2:3], off
	global_load_dwordx4 v[36:39], v[6:7], off
	v_or_b32_e32 v2, s18, v64
	v_mov_b32_e32 v3, s19
	v_lshlrev_b64 v[2:3], 11, v[2:3]
	s_mov_b32 s1, 0
	v_lshl_add_u64 v[2:3], s[12:13], 0, v[2:3]
	s_lshl_b32 s0, s20, 8
	v_lshlrev_b32_e32 v68, 3, v8
	v_lshl_add_u64 v[2:3], v[2:3], 0, s[0:1]
	v_ashrrev_i32_e32 v69, 31, v68
	v_lshl_add_u64 v[2:3], v[68:69], 1, v[2:3]
	global_load_dwordx4 v[40:43], v[2:3], off
	global_load_dwordx4 v[44:47], v[2:3], off offset:64
	global_load_dwordx4 v[48:51], v[2:3], off offset:128
	global_load_dwordx4 v[52:55], v[2:3], off offset:192
	v_and_b32_e32 v2, 0x73, v1
	v_lshrrev_b32_e32 v1, 1, v1
	v_lshlrev_b32_e32 v6, 1, v0
	v_and_b32_e32 v3, 4, v1
	v_and_b32_e32 v6, 8, v6
	v_and_b32_e32 v7, 31, v0
	v_and_b32_e32 v1, 0x60, v1
	v_or3_b32 v2, v2, v3, v6
	v_bfe_u32 v6, v0, 5, 1
	v_or_b32_e32 v0, v1, v7
	v_add_u32_e32 v9, 0, v4
	v_lshl_add_u64 v[70:71], s[16:17], 0, v[4:5]
	v_mul_u32_u24_e32 v10, 0x110, v0
	v_and_b32_e32 v0, 0xffffffe0, v66
	v_lshlrev_b32_e32 v4, 7, v1
	v_lshl_add_u32 v65, v2, 1, 0
	v_lshl_add_u64 v[2:3], s[26:27], 0, v[4:5]
	v_ashrrev_i32_e32 v1, 31, v0
	v_lshl_add_u64 v[0:1], v[0:1], 1, v[2:3]
	v_lshlrev_b32_e32 v4, 1, v7
	v_lshl_add_u64 v[0:1], v[0:1], 0, v[4:5]
	v_lshlrev_b32_e32 v2, 9, v6
	v_mov_b32_e32 v3, v5
	v_lshlrev_b32_e32 v11, 4, v6
	v_lshl_add_u64 v[0:1], v[0:1], 0, v[2:3]
	s_mov_b64 s[16:17], 0xa900000
	s_movk_i32 s0, 0x90
	v_lshl_add_u64 v[72:73], v[0:1], 0, s[16:17]
	v_add3_u32 v0, v10, v11, 0
	v_mul_lo_u32 v7, v66, s0
	s_movk_i32 s0, 0x880
	v_add_u32_e32 v76, 0x4800, v0
	v_lshlrev_b32_e32 v0, 1, v66
	v_mul_lo_u32 v75, v8, s0
	v_and_b32_e32 v0, 0xffffffc0, v0
	s_movk_i32 s0, 0x240
	v_mad_u32_u24 v0, v6, s0, v0
	v_lshlrev_b32_e32 v74, 2, v6
	v_add_u32_e32 v8, 0x2200, v75
	v_or_b32_e32 v0, v0, v4
	v_xor_b32_e32 v77, 0x64, v74
	v_add_u32_e32 v78, 0, v0
	v_add_u32_e32 v79, v9, v7
	v_add_u32_e32 v80, v65, v8
	s_mov_b32 s9, 0x3fb8aa3b
	s_mov_b32 s20, 0xc2ce8ed0
	s_mov_b32 s21, 0x42b17218
	v_mov_b32_e32 v81, 0x7f800000
	s_mov_b32 s16, s64
.LBB0_748:
	s_add_i32 s22, s16, s66
	s_cmpk_gt_i32 s22, 0x3ff
	s_cselect_b32 s67, 1, 0
	s_and_b32 s68, s22, 0x60
	s_cselect_b32 s68, 0, 1
	s_cmp_eq_u32 s28, 0x100
	s_cselect_b32 s67, s68, s67
	s_cmp_lg_u32 s67, 0
	s_cselect_b64 s[18:19], -1, 0
	v_add_u32_e32 v0, v65, v75
	s_and_b64 vcc, exec, s[18:19]
	s_waitcnt vmcnt(5)
	ds_write_b128 v79, v[32:35]
	s_waitcnt vmcnt(4)
	ds_write_b128 v79, v[36:39] offset:9216
	s_waitcnt vmcnt(3)
	ds_write_b16 v0, v40 offset:18432
	ds_write_b16_d16_hi v0, v40 offset:18704
	ds_write_b16 v0, v41 offset:18976
	ds_write_b16_d16_hi v0, v41 offset:19248
	ds_write_b16 v0, v42 offset:19520
	ds_write_b16_d16_hi v0, v42 offset:19792
	ds_write_b16 v0, v43 offset:20064
	ds_write_b16_d16_hi v0, v43 offset:20336
	s_waitcnt vmcnt(2)
	ds_write_b16 v80, v44 offset:18432
	ds_write_b16_d16_hi v80, v44 offset:18704
	ds_write_b16 v80, v45 offset:18976
	ds_write_b16_d16_hi v80, v45 offset:19248
	ds_write_b16 v80, v46 offset:19520
	ds_write_b16_d16_hi v80, v46 offset:19792
	ds_write_b16 v80, v47 offset:20064
	ds_write_b16_d16_hi v80, v47 offset:20336
	s_waitcnt vmcnt(1)
	ds_write_b16 v80, v48 offset:27136
	ds_write_b16_d16_hi v80, v48 offset:27408
	ds_write_b16 v80, v49 offset:27680
	ds_write_b16_d16_hi v80, v49 offset:27952
	ds_write_b16 v80, v50 offset:28224
	ds_write_b16_d16_hi v80, v50 offset:28496
	ds_write_b16 v80, v51 offset:28768
	ds_write_b16_d16_hi v80, v51 offset:29040
	s_waitcnt vmcnt(0)
	ds_write_b16 v80, v52 offset:35840
	ds_write_b16_d16_hi v80, v52 offset:36112
	ds_write_b16 v80, v53 offset:36384
	ds_write_b16_d16_hi v80, v53 offset:36656
	ds_write_b16 v80, v54 offset:36928
	ds_write_b16_d16_hi v80, v54 offset:37200
	ds_write_b16 v80, v55 offset:37472
	ds_write_b16_d16_hi v80, v55 offset:37744
	s_waitcnt lgkmcnt(0)
	s_barrier
	s_cbranch_vccnz .LBB0_750
	s_ashr_i32 s38, s22, 9
	s_ashr_i32 s39, s38, 31
	s_lshl_b32 s0, s22, 7
	s_lshl_b64 s[38:39], s[38:39], 13
	s_and_b32 s0, s0, 0x1f80
	s_bfe_u32 s17, s22, 0x30006
	s_or_b32 s38, s38, s0
	v_lshl_add_u64 v[0:1], s[38:39], 0, v[66:67]
	s_lshl_b32 s0, s17, 7
	v_lshl_add_u64 v[2:3], v[70:71], 0, s[0:1]
	v_lshlrev_b64 v[0:1], 10, v[0:1]
	v_lshl_add_u64 v[0:1], v[2:3], 0, v[0:1]
	v_add_co_u32_e32 v2, vcc, s8, v0
	s_lshl_b32 s0, s17, 8
	s_nop 0
	v_addc_co_u32_e32 v3, vcc, 0, v1, vcc
	global_load_dwordx4 v[32:35], v[0:1], off
	global_load_dwordx4 v[36:39], v[2:3], off
	v_mov_b32_e32 v1, s39
	v_or_b32_e32 v0, s38, v64
	v_lshlrev_b64 v[0:1], 11, v[0:1]
	v_lshl_add_u64 v[0:1], s[12:13], 0, v[0:1]
	v_lshl_add_u64 v[0:1], v[0:1], 0, s[0:1]
	v_lshl_add_u64 v[0:1], v[68:69], 1, v[0:1]
	global_load_dwordx4 v[40:43], v[0:1], off
	global_load_dwordx4 v[44:47], v[0:1], off offset:64
	global_load_dwordx4 v[48:51], v[0:1], off offset:128
	global_load_dwordx4 v[52:55], v[0:1], off offset:192

.LBB0_785:
	s_andn2_saveexec_b64 s[8:9], s[18:19]
	s_cbranch_execz .LBB0_805
	s_mov_b64 s[18:19], exec
	v_mov_b32_e32 v1, 0x20008
	ds_read_b32 v1, v1
	s_waitcnt lgkmcnt(0)
	s_nop 0
	v_readfirstlane_b32 s32, v1
	s_nop 3
	s_cmp_eq_u32 s32, 0
	s_cbranch_scc1 .Lmy_fullbar_1
	v_mov_b32_e32 v1, 0x2000
	v_mov_b32_e32 v3, 1
	global_atomic_add v1, v3, s[16:17] offset:1024
	buffer_inv sc1
	s_waitcnt vmcnt(0)
	s_branch .LBB0_805
.Lmy_fullbar_1:
	buffer_wbl2 sc1
	buffer_inv sc1
	s_waitcnt lgkmcnt(0)
	s_waitcnt vmcnt(0)
	v_mbcnt_lo_u32_b32 v1, s18, 0
	v_mbcnt_hi_u32_b32 v1, s19, v1
	v_cmp_eq_u32_e32 vcc, 0, v1
	s_and_saveexec_b64 s[20:21], vcc
	s_cbranch_execz .LBB0_788
	s_bcnt1_i32_b64 s8, s[18:19]
	v_mov_b32_e32 v2, 0xfe03000
	v_mov_b32_e32 v3, s8
	global_atomic_add v2, v2, v3, s[26:27] offset:1024 sc0

.LBB0_805:
	s_or_b64 exec, exec, s[0:1]
	s_add_u32 s18, s26, 0xa900000
	s_addc_u32 s19, s27, 0
	s_and_b32 s64, s2, 7
	s_lshl_b32 s64, s64, 5
	s_lshr_b32 s67, s2, 3
	s_or_b32 s64, s64, s67
	s_lshl_b32 s64, s64, 9
	s_cmp_eq_u32 s28, 0x100
	s_cselect_b32 s64, s64, s3
	s_add_i32 s0, s33, s64
	s_waitcnt lgkmcnt(0)
	s_barrier
	v_mbcnt_lo_u32_b32 v0, -1, 0
	v_mbcnt_hi_u32_b32 v0, -1, v0
	s_nop 0
	v_add_u32_e32 v4, s0, v0
	s_mov_b32 s0, 0x40000
	v_cmp_gt_i32_e32 vcc, s0, v4
	s_and_saveexec_b64 s[16:17], vcc
	s_cbranch_execz .LBB0_810
	s_mov_b64 s[20:21], 0
	s_mov_b32 s3, 0x20000
	v_mov_b32_e32 v5, s53
	v_mov_b32_e32 v6, s51
	v_mov_b32_e32 v7, s52
	v_mov_b32_e32 v8, s50
	v_mov_b32_e32 v1, 0
	s_mov_b32 s8, 0x3fb8aa3b
	s_mov_b32 s9, 0xc2ce8ed0
	s_mov_b32 s22, 0x42b17218
	v_mov_b32_e32 v9, 0x7f800000
	s_mov_b32 s23, 0x3fffff0
	s_mov_b32 s35, 0x3ffff

.LBB0_842:
	s_andn2_saveexec_b64 s[8:9], s[20:21]
	s_cbranch_execz .LBB0_862
	s_mov_b64 s[20:21], exec
	v_mov_b32_e32 v1, 0x20008
	ds_read_b32 v1, v1
	s_waitcnt lgkmcnt(0)
	s_nop 0
	v_readfirstlane_b32 s32, v1
	s_nop 3
	s_cmp_eq_u32 s32, 0
	s_cbranch_scc1 .Lmy_fullbar_2
	v_mov_b32_e32 v1, 0x2000
	v_mov_b32_e32 v3, 1
	global_atomic_add v1, v3, s[16:17] offset:1024
	buffer_inv sc1
	s_waitcnt vmcnt(0)
	s_branch .LBB0_862

.LBB0_862:
	s_or_b64 exec, exec, s[0:1]
	s_add_u32 s16, s26, 0xde00000
	s_addc_u32 s17, s27, 0
	s_add_u32 s20, s26, 0x8900000
	s_addc_u32 s21, s27, 0
	s_andn2_b64 vcc, exec, s[6:7]
	s_waitcnt lgkmcnt(0)
	s_barrier
	v_mbcnt_lo_u32_b32 v0, -1, 0
	v_mbcnt_hi_u32_b32 v0, -1, v0
	s_cbranch_vccnz .LBB0_871
	s_and_b32 s64, s2, 7
	s_lshl_b32 s64, s64, 7
	s_lshr_b32 s67, s2, 3
	s_or_b32 s64, s64, s67
	s_mov_b32 s66, 32
	s_cmp_eq_u32 s28, 0x100
	s_cselect_b32 s64, s64, s2
	s_cselect_b32 s66, s66, s28
	s_ashr_i32 s65, s64, 31
	s_add_u32 s6, s26, 0x5900000
	s_addc_u32 s7, s27, 0
	s_ashr_i32 s0, s64, 9
	s_and_b32 s3, s64, 63
	s_ashr_i32 s1, s0, 31
	v_add_u32_e32 v1, s33, v0
	s_bfe_u32 s34, s64, 0x30006
	s_lshl_b64 s[8:9], s[0:1], 13
	s_lshl_b32 s0, s3, 7
	v_ashrrev_i32_e32 v106, 3, v1
	s_or_b32 s8, s8, s0
	s_lshl_b32 s0, s34, 7
	v_ashrrev_i32_e32 v107, 31, v106
	s_add_u32 s22, s6, s0
	v_lshlrev_b32_e32 v4, 4, v0
	v_lshl_add_u64 v[2:3], s[8:9], 0, v[106:107]
	s_addc_u32 s23, s7, 0
	v_and_b32_e32 v108, 0x70, v4
	v_mov_b32_e32 v109, 0
	v_lshl_add_u64 v[4:5], s[22:23], 0, v[108:109]
	v_lshlrev_b64 v[2:3], 10, v[2:3]
	v_lshl_add_u64 v[2:3], v[4:5], 0, v[2:3]
	s_mov_b32 s23, 0x10000
	v_and_b32_e32 v104, 0x7f, v1
	v_add_co_u32_e32 v4, vcc, s23, v2
	v_ashrrev_i32_e32 v12, 7, v1
	s_nop 0
	v_addc_co_u32_e32 v5, vcc, 0, v3, vcc
	global_load_dwordx4 v[48:51], v[2:3], off
	global_load_dwordx4 v[52:55], v[4:5], off
	v_or_b32_e32 v2, s8, v104
	v_mov_b32_e32 v3, s9
	v_lshlrev_b64 v[2:3], 11, v[2:3]
	s_mov_b32 s1, 0
	v_lshl_add_u64 v[2:3], s[12:13], 0, v[2:3]
	s_lshl_b32 s0, s34, 8
	v_lshlrev_b32_e32 v110, 3, v12
	s_ashr_i32 s3, s2, 31
	v_lshl_add_u64 v[2:3], v[2:3], 0, s[0:1]
	v_ashrrev_i32_e32 v111, 31, v110
	s_lshl_b64 s[8:9], s[64:65], 14
	v_lshl_add_u64 v[2:3], v[110:111], 1, v[2:3]
	s_add_u32 s8, s18, s8
	global_load_dwordx4 v[56:59], v[2:3], off
	global_load_dwordx4 v[60:63], v[2:3], off offset:64
	global_load_dwordx4 v[64:67], v[2:3], off offset:128
	global_load_dwordx4 v[68:71], v[2:3], off offset:192
	s_addc_u32 s9, s19, s9
	s_add_i32 s34, s64, 0x400
	v_lshlrev_b32_e32 v2, 6, v106
	s_ashr_i32 s35, s34, 31
	v_ashrrev_i32_e32 v3, 31, v2
	s_lshl_b64 s[34:35], s[34:35], 14
	v_lshlrev_b64 v[112:113], 1, v[2:3]
	v_add_u32_e32 v2, 0x1000, v2
	s_add_u32 s34, s18, s34
	v_ashrrev_i32_e32 v3, 31, v2
	s_addc_u32 s35, s19, s35
	v_lshl_add_u64 v[4:5], s[8:9], 0, v[108:109]
	v_lshlrev_b64 v[114:115], 1, v[2:3]
	v_lshl_add_u64 v[6:7], s[34:35], 0, v[108:109]
	v_lshl_add_u64 v[8:9], v[4:5], 0, v[112:113]
	v_lshl_add_u64 v[2:3], v[4:5], 0, v[114:115]
	v_lshl_add_u64 v[10:11], v[6:7], 0, v[112:113]
	global_load_dwordx4 v[72:75], v[8:9], off
	global_load_dwordx4 v[76:79], v[10:11], off
	v_lshl_add_u64 v[4:5], v[6:7], 0, v[114:115]
	global_load_dwordx4 v[80:83], v[2:3], off
	global_load_dwordx4 v[84:87], v[4:5], off
	v_lshrrev_b32_e32 v3, 1, v0
	v_lshlrev_b32_e32 v4, 1, v0
	v_and_b32_e32 v2, 0x73, v1
	v_and_b32_e32 v3, 4, v3
	v_and_b32_e32 v4, 8, v4
	v_ashrrev_i32_e32 v5, 6, v1
	v_ashrrev_i32_e32 v1, 2, v1
	v_or3_b32 v2, v2, v3, v4
	v_and_b32_e32 v4, 31, v0
	v_and_b32_e32 v10, 0xffffffc0, v1
	v_or_b32_e32 v11, v10, v4
	s_movk_i32 s8, 0x90
	s_add_i32 s3, 0, 0x11800
	v_mul_lo_u32 v11, v11, s8
	v_add_u32_e32 v8, s3, v108
	v_lshl_add_u32 v105, v2, 1, 0
	v_lshlrev_b32_e32 v2, 5, v5
	v_add_u32_e32 v13, 0, v11
	v_add_u32_e32 v11, s3, v11
	s_movk_i32 s3, 0x80
	s_add_i32 s0, 0, 0x16000
	v_and_b32_e32 v9, 0x60, v2
	v_bitop3_b32 v2, v2, s3, v4 bitop3:0x36
	v_lshl_add_u32 v6, v4, 2, s0
	v_lshl_add_u32 v130, v2, 2, s0
	s_movk_i32 s0, 0x880
	v_or_b32_e32 v120, v9, v4
	v_mul_lo_u32 v131, v12, s0
	v_lshrrev_b32_e32 v1, 6, v1
	s_movk_i32 s0, 0x4400
	v_bfe_u32 v3, v0, 5, 1
	v_add_u32_e32 v15, 1, v120
	v_mul_lo_u32 v1, v1, s0
	s_movk_i32 s0, 0x110
	v_lshlrev_b32_e32 v14, 4, v3
	v_cvt_f32_ubyte0_e32 v122, v15
	v_mul_u32_u24_e32 v15, 0x90, v4
	v_mad_u32_u24 v1, v4, s0, v1
	v_add_u32_e32 v7, 0, v108
	v_lshl_add_u64 v[116:117], s[6:7], 0, v[108:109]
	v_lshlrev_b32_e32 v0, 3, v3
	v_sub_u32_e32 v16, 0x80, v120
	v_add3_u32 v121, 0, v15, v14
	v_mul_i32_i24_e32 v15, -4, v3
	v_cmp_eq_u32_e64 s[6:7], 0, v3
	v_lshlrev_b32_e32 v5, 7, v5
	v_lshl_or_b32 v124, v3, 2, v10
	v_mul_lo_u32 v2, v106, s8
	v_add_u32_e32 v3, 0x2200, v131
	v_add3_u32 v1, v1, v14, 0
	v_lshl_add_u64 v[118:119], s[18:19], 0, v[108:109]
	v_cvt_f32_ubyte0_e32 v123, v16
	v_ashrrev_i32_e32 v125, 31, v10
	v_add3_u32 v132, v15, v9, v4
	v_add_u32_e32 v133, 0x4800, v1
	v_add_u32_e32 v134, v7, v2
	v_add_u32_e32 v135, v8, v2
	v_add_u32_e32 v136, v105, v3
	s_mov_b32 s3, 0x3fb8aa3b
	s_mov_b32 s42, 0xc2ce8ed0
	s_mov_b32 s43, 0x42b17218
	v_lshlrev_b32_e32 v108, 1, v0
	v_add_u32_e32 v137, v13, v14
	s_mov_b32 s22, 0xbfb8aa3b
	v_add_u32_e32 v138, v11, v14
	v_add_u32_e32 v139, v6, v5
	v_mov_b32_e32 v140, 0x358637bd
	s_mov_b32 s44, 0x800000
	v_mov_b32_e32 v141, 0x7f800000
	s_mov_b32 s8, s64
	s_branch .LBB0_865

.LBB0_865:
	s_add_i32 s34, s8, s66
	s_cmpk_gt_i32 s34, 0x3ff
	s_cselect_b32 s67, 1, 0
	s_and_b32 s68, s34, 0x60
	s_cselect_b32 s68, 0, 1
	s_cmp_eq_u32 s28, 0x100
	s_cselect_b32 s67, s68, s67
	s_cmp_lg_u32 s67, 0
	s_cselect_b64 s[38:39], -1, 0
	v_add_u32_e32 v0, v105, v131
	s_and_b64 vcc, exec, s[38:39]
	s_waitcnt vmcnt(9)
	ds_write_b128 v134, v[48:51]
	s_waitcnt vmcnt(3)
	ds_write_b128 v134, v[72:75] offset:53248
	s_waitcnt vmcnt(2)
	ds_write_b128 v135, v[76:79]
	ds_write_b128 v134, v[52:55] offset:9216
	s_waitcnt vmcnt(1)
	ds_write_b128 v134, v[80:83] offset:62464
	s_waitcnt vmcnt(0)
	ds_write_b128 v135, v[84:87] offset:9216
	ds_write_b16 v0, v56 offset:18432
	ds_write_b16_d16_hi v0, v56 offset:18704
	ds_write_b16 v0, v57 offset:18976
	ds_write_b16_d16_hi v0, v57 offset:19248
	ds_write_b16 v0, v58 offset:19520
	ds_write_b16_d16_hi v0, v58 offset:19792
	ds_write_b16 v0, v59 offset:20064
	ds_write_b16_d16_hi v0, v59 offset:20336
	ds_write_b16 v136, v60 offset:18432
	ds_write_b16_d16_hi v136, v60 offset:18704
	ds_write_b16 v136, v61 offset:18976
	ds_write_b16_d16_hi v136, v61 offset:19248
	ds_write_b16 v136, v62 offset:19520
	ds_write_b16_d16_hi v136, v62 offset:19792
	ds_write_b16 v136, v63 offset:20064
	ds_write_b16_d16_hi v136, v63 offset:20336
	ds_write_b16 v136, v64 offset:27136
	ds_write_b16_d16_hi v136, v64 offset:27408
	ds_write_b16 v136, v65 offset:27680
	ds_write_b16_d16_hi v136, v65 offset:27952
	ds_write_b16 v136, v66 offset:28224
	ds_write_b16_d16_hi v136, v66 offset:28496
	ds_write_b16 v136, v67 offset:28768
	ds_write_b16_d16_hi v136, v67 offset:29040
	ds_write_b16 v136, v68 offset:35840
	ds_write_b16_d16_hi v136, v68 offset:36112
	ds_write_b16 v136, v69 offset:36384
	ds_write_b16_d16_hi v136, v69 offset:36656
	ds_write_b16 v136, v70 offset:36928
	ds_write_b16_d16_hi v136, v70 offset:37200
	ds_write_b16 v136, v71 offset:37472
	ds_write_b16_d16_hi v136, v71 offset:37744
	s_waitcnt lgkmcnt(0)
	s_barrier
	s_cbranch_vccnz .LBB0_867
	s_ashr_i32 s40, s34, 9
	s_and_b32 s0, s34, 63
	s_ashr_i32 s41, s40, 31
	s_lshl_b64 s[40:41], s[40:41], 13
	s_lshl_b32 s0, s0, 7
	s_bfe_u32 s9, s34, 0x30006
	s_or_b32 s40, s40, s0
	v_lshl_add_u64 v[0:1], s[40:41], 0, v[106:107]
	s_lshl_b32 s0, s9, 7
	v_lshl_add_u64 v[2:3], v[116:117], 0, s[0:1]
	v_lshlrev_b64 v[0:1], 10, v[0:1]
	v_lshl_add_u64 v[0:1], v[2:3], 0, v[0:1]
	v_add_co_u32_e32 v2, vcc, s23, v0
	s_lshl_b32 s0, s9, 8
	s_nop 0
	v_addc_co_u32_e32 v3, vcc, 0, v1, vcc
	global_load_dwordx4 v[48:51], v[0:1], off
	global_load_dwordx4 v[52:55], v[2:3], off
	v_mov_b32_e32 v1, s41
	v_or_b32_e32 v0, s40, v104
	v_lshlrev_b64 v[0:1], 11, v[0:1]
	v_lshl_add_u64 v[0:1], s[12:13], 0, v[0:1]
	v_lshl_add_u64 v[0:1], v[0:1], 0, s[0:1]
	s_ashr_i32 s35, s34, 31
	s_add_i32 s46, s34, 0x400
	v_lshl_add_u64 v[0:1], v[110:111], 1, v[0:1]
	s_lshl_b64 s[40:41], s[34:35], 14
	s_ashr_i32 s47, s46, 31
	global_load_dwordx4 v[56:59], v[0:1], off
	global_load_dwordx4 v[60:63], v[0:1], off offset:64
	global_load_dwordx4 v[64:67], v[0:1], off offset:128
	global_load_dwordx4 v[68:71], v[0:1], off offset:192
	s_lshl_b64 s[46:47], s[46:47], 14
	v_lshl_add_u64 v[0:1], v[118:119], 0, s[40:41]
	v_lshl_add_u64 v[2:3], v[118:119], 0, s[46:47]
	v_lshl_add_u64 v[4:5], v[0:1], 0, v[112:113]
	v_lshl_add_u64 v[0:1], v[0:1], 0, v[114:115]
	v_lshl_add_u64 v[6:7], v[2:3], 0, v[112:113]
	global_load_dwordx4 v[72:75], v[4:5], off
	global_load_dwordx4 v[76:79], v[6:7], off
	v_lshl_add_u64 v[2:3], v[2:3], 0, v[114:115]
	global_load_dwordx4 v[80:83], v[0:1], off
	global_load_dwordx4 v[84:87], v[2:3], off
